# attention tile max as one dependent v_max3 chain (carried operand forwarded) instead of a tree
# speedup vs baseline: 1.0061x; 1.0044x over previous
.Latt_loop:
	s_waitcnt vmcnt(0)
	s_barrier
	ds_read_b128 v[64:67], v173 offset:24576
	ds_read_b128 v[68:71], v173 offset:28672
	s_mov_b32 m0, s44
	ds_read_b128 v[72:75], v171 offset:24576
	global_load_lds_dwordx4 v200, s[40:41]
	s_add_u32 m0, s44, 0x400
	ds_read_b128 v[76:79], v171 offset:28672
	global_load_lds_dwordx4 v190, s[40:41]
	s_mov_b32 m0, s45
	ds_read_b128 v[216:219], v169 offset:24576
	global_load_lds_dwordx4 v192, s[42:43]
	s_add_u32 m0, s45, 0x400
	ds_read_b128 v[220:223], v169 offset:28672
	global_load_lds_dwordx4 v194, s[42:43]
	s_add_u32 m0, s45, 0x800
	ds_read_b128 v[224:227], v167 offset:24576
	global_load_lds_dwordx4 v196, s[42:43]
	s_add_u32 m0, s45, 0xc00
	ds_read_b128 v[228:231], v167 offset:28672
	global_load_lds_dwordx4 v198, s[42:43]
	ds_read_b128 v[232:235], v173 offset:32768
	ds_read_b128 v[236:239], v173 offset:36864
	ds_read_b128 v[240:243], v173 offset:40960
	ds_read_b128 v[244:247], v173 offset:45056
	s_add_u32 s40, s40, 0x18000
	s_addc_u32 s41, s41, 0
	s_add_u32 s42, s42, 0x80
	s_addc_u32 s43, s43, 0
	s_waitcnt lgkmcnt(11)
	v_mfma_f32_32x32x16_bf16 v[112:127], v[64:67], v[140:143], v[96:111]
	ds_read_b128 v[64:67], v171 offset:32768
	s_waitcnt lgkmcnt(11)
	v_mfma_f32_32x32x16_bf16 v[80:95], v[68:71], v[140:143], v[96:111]
	ds_read_b128 v[68:71], v171 offset:36864
	s_waitcnt lgkmcnt(11)
	v_mfma_f32_32x32x16_bf16 v[112:127], v[72:75], v[136:139], v[112:127]
	ds_read_b128 v[72:75], v171 offset:40960
	s_waitcnt lgkmcnt(11)
	v_mfma_f32_32x32x16_bf16 v[80:95], v[76:79], v[136:139], v[80:95]
	ds_read_b128 v[76:79], v171 offset:45056
	s_waitcnt lgkmcnt(11)
	v_mfma_f32_32x32x16_bf16 v[112:127], v[216:219], v[132:135], v[112:127]
	ds_read_b128 v[216:219], v169 offset:32768
	s_waitcnt lgkmcnt(11)
	v_mfma_f32_32x32x16_bf16 v[80:95], v[220:223], v[132:135], v[80:95]
	ds_read_b128 v[220:223], v169 offset:36864
	s_waitcnt lgkmcnt(11)
	v_mfma_f32_32x32x16_bf16 v[112:127], v[224:227], v[128:131], v[112:127]
	ds_read_b128 v[224:227], v169 offset:40960
	s_waitcnt lgkmcnt(11)
	v_mfma_f32_32x32x16_bf16 v[80:95], v[228:231], v[128:131], v[80:95]
	ds_read_b128 v[228:231], v169 offset:45056
	s_nop 7
	s_nop 3
	v_max3_f32 v175, v112, v113, v114
	v_max3_f32 v175, v175, v115, v116
	v_max3_f32 v175, v175, v117, v118
	v_max3_f32 v175, v175, v119, v120
	v_max3_f32 v175, v175, v121, v122
	v_max3_f32 v175, v175, v123, v124
	v_max3_f32 v175, v175, v125, v126
	v_max3_f32 v175, v175, v127, v80
	v_max3_f32 v175, v175, v81, v82
	v_max3_f32 v175, v175, v83, v84
	v_max3_f32 v175, v175, v85, v86
	v_max3_f32 v175, v175, v87, v88
	v_max3_f32 v175, v175, v89, v90
	v_max3_f32 v175, v175, v91, v92
	v_max3_f32 v175, v175, v93, v94
	v_max_f32_e32 v175, v175, v95
	v_cmp_lt_f32_e32 vcc, 0x41000000, v175
	s_cbranch_vccnz .Latt_resc_a
.Latt_cont_a:
	v_exp_f32_e32 v112, v112
	v_exp_f32_e32 v113, v113
	v_exp_f32_e32 v114, v114
	v_exp_f32_e32 v115, v115
	v_exp_f32_e32 v116, v116
	v_exp_f32_e32 v117, v117
	v_exp_f32_e32 v118, v118
	v_exp_f32_e32 v119, v119
	v_add_f32_e32 v189, v189, v112
	v_add_f32_e32 v189, v189, v113
	v_add_f32_e32 v189, v189, v114
	v_add_f32_e32 v189, v189, v115
	v_add_f32_e32 v189, v189, v116
	v_add_f32_e32 v189, v189, v117
	v_add_f32_e32 v189, v189, v118
	v_add_f32_e32 v189, v189, v119
	v_cvt_pk_bf16_f32 v112, v112, v113
	v_cvt_pk_bf16_f32 v113, v114, v115
	v_cvt_pk_bf16_f32 v114, v116, v117
	v_cvt_pk_bf16_f32 v115, v118, v119
	v_exp_f32_e32 v120, v120
	v_exp_f32_e32 v121, v121
	s_waitcnt lgkmcnt(8)
	v_mfma_f32_32x32x16_bf16 v[48:63], v[232:235], v[112:115], v[48:63]
	v_exp_f32_e32 v122, v122
	v_exp_f32_e32 v123, v123
	v_exp_f32_e32 v124, v124
	v_mfma_f32_32x32x16_bf16 v[32:47], v[236:239], v[112:115], v[32:47]
	v_exp_f32_e32 v125, v125
	v_exp_f32_e32 v126, v126
	v_exp_f32_e32 v127, v127
	v_mfma_f32_32x32x16_bf16 v[16:31], v[240:243], v[112:115], v[16:31]
	v_add_f32_e32 v189, v189, v120
	v_add_f32_e32 v189, v189, v121
	v_add_f32_e32 v189, v189, v122
	v_add_f32_e32 v189, v189, v123
	v_add_f32_e32 v189, v189, v124
	v_add_f32_e32 v189, v189, v125
	v_mfma_f32_32x32x16_bf16 v[0:15], v[244:247], v[112:115], v[0:15]
	ds_read_b128 v[232:235], v167 offset:32768
	ds_read_b128 v[236:239], v167 offset:36864
	ds_read_b128 v[240:243], v167 offset:40960
	ds_read_b128 v[244:247], v167 offset:45056
	v_add_f32_e32 v189, v189, v126
	v_add_f32_e32 v189, v189, v127
	v_cvt_pk_bf16_f32 v116, v120, v121
	v_cvt_pk_bf16_f32 v117, v122, v123
	v_cvt_pk_bf16_f32 v118, v124, v125
	v_cvt_pk_bf16_f32 v119, v126, v127
	s_nop 0
	s_waitcnt lgkmcnt(8)
	v_mfma_f32_32x32x16_bf16 v[48:63], v[64:67], v[116:119], v[48:63]
	v_exp_f32_e32 v80, v80
	v_exp_f32_e32 v81, v81
	v_exp_f32_e32 v82, v82
	v_mfma_f32_32x32x16_bf16 v[32:47], v[68:71], v[116:119], v[32:47]
	v_exp_f32_e32 v83, v83
	v_exp_f32_e32 v84, v84
	v_exp_f32_e32 v85, v85
	v_mfma_f32_32x32x16_bf16 v[16:31], v[72:75], v[116:119], v[16:31]
	v_exp_f32_e32 v86, v86
	v_exp_f32_e32 v87, v87
	v_add_f32_e32 v189, v189, v80
	v_add_f32_e32 v189, v189, v81
	v_mfma_f32_32x32x16_bf16 v[0:15], v[76:79], v[116:119], v[0:15]
	v_add_f32_e32 v189, v189, v82
	v_add_f32_e32 v189, v189, v83
	v_add_f32_e32 v189, v189, v84
	v_add_f32_e32 v189, v189, v85
	v_add_f32_e32 v189, v189, v86
	v_add_f32_e32 v189, v189, v87
	v_cvt_pk_bf16_f32 v80, v80, v81
	v_cvt_pk_bf16_f32 v81, v82, v83
	v_cvt_pk_bf16_f32 v82, v84, v85
	v_cvt_pk_bf16_f32 v83, v86, v87
	s_nop 0
	s_waitcnt lgkmcnt(4)
	v_mfma_f32_32x32x16_bf16 v[48:63], v[216:219], v[80:83], v[48:63]
	v_exp_f32_e32 v88, v88
	v_exp_f32_e32 v89, v89
	v_exp_f32_e32 v90, v90
	v_mfma_f32_32x32x16_bf16 v[32:47], v[220:223], v[80:83], v[32:47]
	v_exp_f32_e32 v91, v91
	v_exp_f32_e32 v92, v92
	v_exp_f32_e32 v93, v93
	v_mfma_f32_32x32x16_bf16 v[16:31], v[224:227], v[80:83], v[16:31]
	v_exp_f32_e32 v94, v94
	v_exp_f32_e32 v95, v95
	v_add_f32_e32 v189, v189, v88
	v_add_f32_e32 v189, v189, v89
	v_mfma_f32_32x32x16_bf16 v[0:15], v[228:231], v[80:83], v[0:15]
	v_add_f32_e32 v189, v189, v90
	v_add_f32_e32 v189, v189, v91
	v_add_f32_e32 v189, v189, v92
	v_add_f32_e32 v189, v189, v93
	v_add_f32_e32 v189, v189, v94
	v_add_f32_e32 v189, v189, v95
	v_cvt_pk_bf16_f32 v84, v88, v89
	v_cvt_pk_bf16_f32 v85, v90, v91
	v_cvt_pk_bf16_f32 v86, v92, v93
	v_cvt_pk_bf16_f32 v87, v94, v95
	s_nop 0
	s_waitcnt lgkmcnt(0)
	v_mfma_f32_32x32x16_bf16 v[48:63], v[232:235], v[84:87], v[48:63]
	v_mfma_f32_32x32x16_bf16 v[32:47], v[236:239], v[84:87], v[32:47]
	v_mfma_f32_32x32x16_bf16 v[16:31], v[240:243], v[84:87], v[16:31]
	v_mfma_f32_32x32x16_bf16 v[0:15], v[244:247], v[84:87], v[0:15]
	s_waitcnt vmcnt(0)
	s_barrier
	ds_read_b128 v[64:67], v173 offset:0
	ds_read_b128 v[68:71], v173 offset:4096
	s_add_u32 m0, s44, 0x6000
	ds_read_b128 v[72:75], v171 offset:0
	global_load_lds_dwordx4 v200, s[40:41]
	s_add_u32 m0, s44, 0x6400
	ds_read_b128 v[76:79], v171 offset:4096
	global_load_lds_dwordx4 v190, s[40:41]
	s_add_u32 m0, s45, 0x6000
	ds_read_b128 v[216:219], v169 offset:0
	global_load_lds_dwordx4 v192, s[42:43]
	s_add_u32 m0, s45, 0x6400
	ds_read_b128 v[220:223], v169 offset:4096
	global_load_lds_dwordx4 v194, s[42:43]
	s_add_u32 m0, s45, 0x6800
	ds_read_b128 v[224:227], v167 offset:0
	global_load_lds_dwordx4 v196, s[42:43]
	s_add_u32 m0, s45, 0x6c00
	ds_read_b128 v[228:231], v167 offset:4096
	global_load_lds_dwordx4 v198, s[42:43]
	ds_read_b128 v[232:235], v173 offset:8192
	ds_read_b128 v[236:239], v173 offset:12288
	ds_read_b128 v[240:243], v173 offset:16384
	ds_read_b128 v[244:247], v173 offset:20480
	s_add_u32 s40, s40, 0x18000
	s_addc_u32 s41, s41, 0
	s_add_u32 s42, s42, 0x80
	s_addc_u32 s43, s43, 0
	s_waitcnt lgkmcnt(11)
	v_mfma_f32_32x32x16_bf16 v[112:127], v[64:67], v[140:143], v[96:111]
	ds_read_b128 v[64:67], v171 offset:8192
	s_waitcnt lgkmcnt(11)
	v_mfma_f32_32x32x16_bf16 v[80:95], v[68:71], v[140:143], v[96:111]
	ds_read_b128 v[68:71], v171 offset:12288
	s_waitcnt lgkmcnt(11)
	v_mfma_f32_32x32x16_bf16 v[112:127], v[72:75], v[136:139], v[112:127]
	ds_read_b128 v[72:75], v171 offset:16384
	s_waitcnt lgkmcnt(11)
	v_mfma_f32_32x32x16_bf16 v[80:95], v[76:79], v[136:139], v[80:95]
	ds_read_b128 v[76:79], v171 offset:20480
	s_waitcnt lgkmcnt(11)
	v_mfma_f32_32x32x16_bf16 v[112:127], v[216:219], v[132:135], v[112:127]
	ds_read_b128 v[216:219], v169 offset:8192
	s_waitcnt lgkmcnt(11)
	v_mfma_f32_32x32x16_bf16 v[80:95], v[220:223], v[132:135], v[80:95]
	ds_read_b128 v[220:223], v169 offset:12288
	s_waitcnt lgkmcnt(11)
	v_mfma_f32_32x32x16_bf16 v[112:127], v[224:227], v[128:131], v[112:127]
	ds_read_b128 v[224:227], v169 offset:16384
	s_waitcnt lgkmcnt(11)
	v_mfma_f32_32x32x16_bf16 v[80:95], v[228:231], v[128:131], v[80:95]
	ds_read_b128 v[228:231], v169 offset:20480
	s_nop 7
	s_nop 3
	v_max3_f32 v175, v112, v113, v114
	v_max3_f32 v175, v175, v115, v116
	v_max3_f32 v175, v175, v117, v118
	v_max3_f32 v175, v175, v119, v120
	v_max3_f32 v175, v175, v121, v122
	v_max3_f32 v175, v175, v123, v124
	v_max3_f32 v175, v175, v125, v126
	v_max3_f32 v175, v175, v127, v80
	v_max3_f32 v175, v175, v81, v82
	v_max3_f32 v175, v175, v83, v84
	v_max3_f32 v175, v175, v85, v86
	v_max3_f32 v175, v175, v87, v88
	v_max3_f32 v175, v175, v89, v90
	v_max3_f32 v175, v175, v91, v92
	v_max3_f32 v175, v175, v93, v94
	v_max_f32_e32 v175, v175, v95
	v_cmp_lt_f32_e32 vcc, 0x41000000, v175
	s_cbranch_vccnz .Latt_resc_b
